# stat-table block moved after first LDS-DMA stage loads (overlap cold latency); hgrn_sample task loads hoisted and batched (was 12 serialized round trips per task)
# speedup vs baseline: 1.0267x; 1.0084x over previous
.LBB0_206:
	s_add_u32 s14, s4, 0xa2c8000
	v_readlane_b32 s8, v255, 19
	s_addc_u32 s15, s5, 0
	s_lshl_b32 s3, s8, 22
	s_add_u32 s3, s4, s3
	s_mov_b32 s10, s8
	s_addc_u32 s8, s5, 0
	s_add_u32 s16, s3, 0x1400000
	v_readlane_b32 s9, v255, 20
	s_addc_u32 s17, s8, 0
	s_lshl_b32 s38, s10, 11
	s_lshl_b64 s[8:9], s[38:39], 2
	s_add_u32 s3, s4, s8
	s_addc_u32 s11, s5, s9
	s_add_u32 s8, s3, 0x6210000
	s_addc_u32 s9, s11, 0
	s_add_u32 s10, s3, 0x6214000
	s_addc_u32 s11, s11, 0
	s_add_u32 s28, s4, 0xc914000
	s_addc_u32 s50, s5, 0
	s_add_u32 s12, s4, 0xc710000
	s_addc_u32 s13, s5, 0
	v_readlane_b32 s4, v252, 48
	v_mov_b32_e32 v17, v213
	v_readlane_b32 s5, v252, 49
	s_waitcnt lgkmcnt(0)
	s_barrier
	s_andn2_b64 vcc, exec, s[4:5]
	v_readfirstlane_b32 s51, v17
	s_cbranch_vccnz .LBB0_232
	v_lshlrev_b32_e32 v2, 4, v17
	v_add_u32_e32 v3, 0x2000, v2
	v_ashrrev_i32_e32 v1, 31, v3
	v_lshrrev_b32_e32 v1, 22, v1
	v_add_u32_e32 v1, v3, v1
	v_ashrrev_i32_e32 v1, 10, v1
	v_mul_i32_i24_e32 v4, 0x400, v1
	v_sub_u32_e32 v3, v3, v4
	v_lshrrev_b32_e32 v4, 4, v3
	v_bitop3_b32 v3, v4, v3, 32 bitop3:0x6c
	v_ashrrev_i32_e32 v4, 31, v3
	v_lshrrev_b32_e32 v4, 26, v4
	v_add_u32_e32 v4, v3, v4
	v_ashrrev_i32_e32 v10, 6, v4
	v_and_b32_e32 v4, 0xc0, v4
	v_sub_u32_e32 v3, v3, v4
	v_ashrrev_i16_sdwa v3, v219, sext(v3) dst_sel:DWORD dst_unused:UNUSED_PAD src0_sel:DWORD src1_sel:BYTE_0
	v_bfe_i32 v12, v3, 0, 16
	v_bfe_i32 v3, v17, 27, 1
	v_lshrrev_b32_e32 v3, 22, v3
	v_add_u32_e32 v3, v2, v3
	v_and_b32_e32 v3, 0xfffffc00, v3
	v_sub_u32_e32 v2, v2, v3
	v_lshrrev_b32_e32 v3, 4, v2
	v_bitop3_b32 v2, v3, v2, 32 bitop3:0x6c
	v_ashrrev_i32_e32 v4, 31, v17
	v_lshlrev_b32_e32 v5, 3, v1
	v_ashrrev_i32_e32 v3, 31, v2
	v_lshrrev_b32_e32 v4, 26, v4
	v_and_b32_e32 v5, 0x1ffff0, v5
	v_lshlrev_b32_e32 v6, 5, v1
	v_lshrrev_b32_e32 v3, 26, v3
	v_add_u32_e32 v4, v17, v4
	v_add_u32_e32 v5, v10, v5
	v_and_b32_e32 v11, 32, v6
	v_add_u32_e32 v3, v2, v3
	v_ashrrev_i32_e32 v14, 6, v4
	s_ashr_i32 s4, s51, 6
	v_lshl_or_b32 v5, v5, 10, v11
	v_ashrrev_i32_e32 v13, 6, v3
	v_lshlrev_b32_e32 v4, 3, v14
	v_and_b32_e32 v3, 0xc0, v3
	s_ashr_i32 s3, s51, 8
	s_lshl_b32 s52, s4, 10
	v_add_lshl_u32 v162, v5, v12, 1
	v_and_b32_e32 v4, 0x1ffff0, v4
	v_lshlrev_b32_e32 v5, 5, v14
	v_sub_u32_e32 v2, v2, v3
	v_readlane_b32 s18, v252, 53
	v_add_u32_e32 v4, v13, v4
	v_and_b32_e32 v15, 32, v5
	v_ashrrev_i16_sdwa v2, v219, sext(v2) dst_sel:DWORD dst_unused:UNUSED_PAD src0_sel:DWORD src1_sel:BYTE_0
	v_readlane_b32 s19, v252, 54
	s_add_u32 s18, s16, s18
	v_lshl_or_b32 v4, v4, 10, v15
	v_bfe_i32 v16, v2, 0, 16
	s_addc_u32 s19, s17, s19
	s_add_i32 s53, s52, 0
	v_add_lshl_u32 v164, v4, v16, 1
	s_add_i32 m0, s53, 0x10000
	v_readlane_b32 s5, v252, 50
	global_load_lds_dwordx4 v164, s[18:19]
	s_add_i32 m0, s53, 0x12000
	s_add_u32 s20, s14, s5
	global_load_lds_dwordx4 v162, s[18:19]
	s_addc_u32 s21, s15, 0
	s_mov_b32 m0, s53
	s_add_i32 s54, s53, 0x2000
	global_load_lds_dwordx4 v164, s[20:21]
	s_mov_b32 m0, s54
	s_add_u32 s36, s18, 0x40000
	global_load_lds_dwordx4 v162, s[20:21]
	s_addc_u32 s37, s19, 0
	s_add_i32 m0, s53, 0x14000
	v_mov_b32_e32 v165, v0
	global_load_lds_dwordx4 v164, s[36:37]
	s_add_i32 m0, s53, 0x16000
	v_mov_b32_e32 v163, v0
	global_load_lds_dwordx4 v162, s[36:37]
	s_add_u32 s36, s20, 0x40000
	s_addc_u32 s37, s21, 0
	s_add_i32 s55, s53, 0x4000
	s_mov_b32 m0, s55
	s_add_i32 s56, s53, 0x6000
	global_load_lds_dwordx4 v164, s[36:37]
	s_mov_b32 m0, s56
	v_lshl_add_u64 v[8:9], s[18:19], 0, v[164:165]
	global_load_lds_dwordx4 v162, s[36:37]
	s_mov_b64 s[100:101], exec
	v_readlane_b32 s98, v254, 59
	v_readlane_b32 s99, v254, 60
	s_and_b64 s[98:99], s[100:101], s[98:99]
	s_mov_b64 exec, s[98:99]
	s_cbranch_execz .Lstat_skip_1
	v_lshl_add_u64 v[134:135], s[6:7], 0, v[198:199]
	global_load_dwordx4 v[100:103], v[134:135], off
	global_load_dwordx4 v[104:107], v[134:135], off offset:16
	global_load_dwordx4 v[108:111], v[134:135], off offset:32
	global_load_dwordx4 v[112:115], v[134:135], off offset:48
	global_load_dwordx4 v[116:119], v[134:135], off offset:64
	global_load_dwordx4 v[120:123], v[134:135], off offset:80
	global_load_dwordx4 v[124:127], v[134:135], off offset:96
	global_load_dwordx4 v[128:131], v[134:135], off offset:112
	s_mov_b32 s98, 0x3a800000
	s_waitcnt vmcnt(0) lgkmcnt(0)
	v_pk_add_f32 v[100:101], v[100:101], v[102:103]
	v_pk_add_f32 v[104:105], v[104:105], v[106:107]
	v_pk_add_f32 v[108:109], v[108:109], v[110:111]
	v_pk_add_f32 v[112:113], v[112:113], v[114:115]
	v_pk_add_f32 v[116:117], v[116:117], v[118:119]
	v_pk_add_f32 v[120:121], v[120:121], v[122:123]
	v_pk_add_f32 v[124:125], v[124:125], v[126:127]
	v_pk_add_f32 v[128:129], v[128:129], v[130:131]
	v_pk_add_f32 v[136:137], v[100:101], 0 op_sel_hi:[1,0]
	s_nop 0
	v_pk_add_f32 v[136:137], v[136:137], v[104:105]
	s_nop 0
	v_pk_add_f32 v[136:137], v[136:137], v[108:109]
	s_nop 0
	v_pk_add_f32 v[136:137], v[136:137], v[112:113]
	s_nop 0
	v_pk_add_f32 v[136:137], v[136:137], v[116:117]
	s_nop 0
	v_pk_add_f32 v[136:137], v[136:137], v[120:121]
	s_nop 0
	v_pk_add_f32 v[136:137], v[136:137], v[124:125]
	s_nop 0
	v_pk_add_f32 v[138:139], v[136:137], v[128:129]
	s_nop 0
	v_pk_mul_f32 v[138:139], v[138:139], s[98:99] op_sel_hi:[1,0]
	s_nop 0
	v_fma_f32 v132, -v138, v138, v139
	v_max_f32_e32 v132, 0, v132
	v_add_f32_e32 v132, 0x3727c5ac, v132
	v_cmp_gt_f32_e32 vcc, 0x800000, v132
	v_mul_f32_e32 v139, 0x4b800000, v132
	s_nop 0
	v_cndmask_b32_e32 v132, v132, v139, vcc
	v_rsq_f32_e32 v132, v132
	s_nop 0
	v_mul_f32_e32 v139, 0x45800000, v132
	v_cndmask_b32_e32 v139, v132, v139, vcc
	ds_write_b64 v217, v[138:139]
.Lstat_skip_1:
	s_or_b64 exec, exec, s[100:101]
.Lstat_done_1:
	v_lshl_add_u64 v[6:7], s[18:19], 0, v[162:163]
	v_lshl_add_u64 v[4:5], s[20:21], 0, v[164:165]
	s_cmp_lg_u32 s3, 1
	v_lshl_add_u64 v[2:3], s[20:21], 0, v[162:163]
	s_cbranch_scc1 .LBB0_209
	s_barrier

.LBB0_385:
	v_readlane_b32 s68, v252, 32
	s_mov_b64 s[6:7], 0x1c00000
	s_and_b64 vcc, exec, s[4:5]
	v_readlane_b32 s72, v252, 36
	v_readlane_b32 s73, v252, 37
	v_readlane_b32 s74, v252, 38
	v_readlane_b32 s75, v252, 39
	v_readlane_b32 s76, v252, 40
	v_readlane_b32 s77, v252, 41
	v_readlane_b32 s78, v252, 42
	v_readlane_b32 s79, v252, 43
	v_readlane_b32 s80, v252, 44
	v_readlane_b32 s81, v252, 45
	v_readlane_b32 s69, v252, 33
	v_readlane_b32 s70, v252, 34
	v_readlane_b32 s71, v252, 35
	v_readlane_b32 s82, v252, 46
	v_readlane_b32 s83, v252, 47
	s_cbranch_vccz .LBB0_1088
	v_readlane_b32 s6, v255, 21
	s_cmp_eq_u32 s6, 0
	s_mov_b64 s[4:5], s[24:25]
	v_readlane_b32 s7, v255, 22
	s_cselect_b64 s[10:11], -1, 0
	s_cmp_lg_u32 s6, 0
	s_cselect_b64 s[6:7], -1, 0
	s_add_u32 s8, s4, 0xc50c000
	v_readlane_b32 s70, v253, 53
	s_addc_u32 s9, s5, 0
	s_and_b64 vcc, exec, s[10:11]
	v_readlane_b32 s71, v253, 54
	v_readlane_b32 s82, v255, 15
	s_mov_b32 s83, 0x800000
	s_cbranch_vccnz .LBB0_390
.LBB0_389:
	s_waitcnt lgkmcnt(0)
	s_barrier
.LBB0_390:
	s_and_b64 s[10:11], exec, s[10:11]
	s_mov_b32 s3, 0x6248000
	s_cselect_b32 s3, s3, 0xa2c8000
	s_add_u32 s18, s4, s3
	v_readlane_b32 s10, v255, 19
	s_addc_u32 s19, s5, 0
	s_lshl_b32 s3, s10, 23
	s_add_u32 s16, s4, s3
	v_readlane_b32 s11, v255, 20
	s_addc_u32 s17, s5, 0
	s_lshl_b32 s38, s10, 12
	s_mov_b32 s14, s10
	s_lshl_b64 s[10:11], s[38:39], 2
	s_add_u32 s3, s4, s10
	s_addc_u32 s13, s5, s11
	s_add_u32 s10, s3, 0x6200000
	s_addc_u32 s11, s13, 0
	s_add_u32 s12, s3, 0x6208000
	s_addc_u32 s13, s13, 0
	s_add_u32 s28, s4, 0xc914000
	s_addc_u32 s58, s5, 0
	s_lshl_b32 s38, s14, 10
	s_lshl_b64 s[14:15], s[38:39], 2
	s_add_u32 s3, s4, s14
	s_addc_u32 s4, s5, s15
	s_add_u32 s14, s3, 0x6244000
	s_addc_u32 s15, s4, 0
	v_readlane_b32 s4, v253, 61
	v_readlane_b32 s5, v253, 62
	v_mov_b32_e32 v18, v213
	s_andn2_b64 vcc, exec, s[4:5]
	v_cndmask_b32_e64 v1, 0, 1, s[4:5]
	v_cmp_ne_u32_e64 s[40:41], 1, v1
	v_readfirstlane_b32 s38, v18
	s_cbranch_vccnz .LBB0_816
	v_lshlrev_b32_e32 v1, 4, v18
	v_add_u32_e32 v2, 0x2000, v1
	v_ashrrev_i32_e32 v3, 31, v2
	v_lshrrev_b32_e32 v3, 22, v3
	v_add_u32_e32 v3, v2, v3
	v_ashrrev_i32_e32 v10, 10, v3
	v_mul_i32_i24_e32 v3, 0x400, v10
	v_sub_u32_e32 v2, v2, v3
	v_lshrrev_b32_e32 v3, 4, v2
	v_bitop3_b32 v2, v3, v2, 32 bitop3:0x6c
	v_ashrrev_i32_e32 v3, 31, v2
	v_lshrrev_b32_e32 v3, 26, v3
	v_add_u32_e32 v3, v2, v3
	v_ashrrev_i32_e32 v11, 6, v3
	v_and_b32_e32 v3, 0xc0, v3
	v_sub_u32_e32 v2, v2, v3
	v_ashrrev_i16_sdwa v2, v219, sext(v2) dst_sel:DWORD dst_unused:UNUSED_PAD src0_sel:DWORD src1_sel:BYTE_0
	v_bfe_i32 v13, v2, 0, 16
	v_bfe_i32 v2, v18, 27, 1
	v_lshrrev_b32_e32 v2, 22, v2
	v_add_u32_e32 v2, v1, v2
	v_and_b32_e32 v2, 0xfffffc00, v2
	v_sub_u32_e32 v1, v1, v2
	v_lshrrev_b32_e32 v2, 4, v1
	v_bitop3_b32 v1, v2, v1, 32 bitop3:0x6c
	v_ashrrev_i32_e32 v3, 31, v18
	v_lshlrev_b32_e32 v4, 3, v10
	v_ashrrev_i32_e32 v2, 31, v1
	v_lshrrev_b32_e32 v3, 26, v3
	v_and_b32_e32 v4, 0x1ffff0, v4
	v_lshlrev_b32_e32 v5, 5, v10
	v_lshrrev_b32_e32 v2, 26, v2
	v_add_u32_e32 v3, v18, v3
	v_add_u32_e32 v4, v11, v4
	v_and_b32_e32 v12, 32, v5
	v_add_u32_e32 v2, v1, v2
	v_ashrrev_i32_e32 v15, 6, v3
	s_ashr_i32 s3, s38, 6
	v_lshl_or_b32 v4, v4, 10, v12
	v_ashrrev_i32_e32 v14, 6, v2
	v_lshlrev_b32_e32 v3, 3, v15
	v_and_b32_e32 v2, 0xc0, v2
	s_ashr_i32 s4, s38, 8
	s_lshl_b32 s59, s3, 10
	v_add_lshl_u32 v182, v4, v13, 1
	v_and_b32_e32 v3, 0x1ffff0, v3
	v_lshlrev_b32_e32 v4, 5, v15
	v_sub_u32_e32 v1, v1, v2
	v_readlane_b32 s20, v252, 53
	v_add_u32_e32 v3, v14, v3
	v_and_b32_e32 v16, 32, v4
	v_ashrrev_i16_sdwa v1, v219, sext(v1) dst_sel:DWORD dst_unused:UNUSED_PAD src0_sel:DWORD src1_sel:BYTE_0
	v_readlane_b32 s21, v252, 54
	s_add_u32 s20, s16, s20
	v_lshl_or_b32 v3, v3, 10, v16
	v_bfe_i32 v17, v1, 0, 16
	s_addc_u32 s21, s17, s21
	s_add_i32 s60, s59, 0
	v_add_lshl_u32 v184, v3, v17, 1
	s_add_i32 m0, s60, 0x10000
	v_readlane_b32 s5, v252, 50
	global_load_lds_dwordx4 v184, s[20:21]
	s_add_i32 m0, s60, 0x12000
	s_add_u32 s48, s18, s5
	global_load_lds_dwordx4 v182, s[20:21]
	s_addc_u32 s49, s19, 0
	s_mov_b32 m0, s60
	s_add_i32 s61, s60, 0x2000
	global_load_lds_dwordx4 v184, s[48:49]
	s_mov_b32 m0, s61
	s_add_u32 s36, s20, 0x40000
	global_load_lds_dwordx4 v182, s[48:49]
	s_addc_u32 s37, s21, 0
	s_add_i32 m0, s60, 0x14000
	v_mov_b32_e32 v185, v0
	global_load_lds_dwordx4 v184, s[36:37]
	s_add_i32 m0, s60, 0x16000
	v_mov_b32_e32 v183, v0
	global_load_lds_dwordx4 v182, s[36:37]
	s_add_u32 s36, s48, 0x40000
	s_addc_u32 s37, s49, 0
	s_add_i32 s62, s60, 0x4000
	s_mov_b32 m0, s62
	s_add_i32 s63, s60, 0x6000
	global_load_lds_dwordx4 v184, s[36:37]
	s_mov_b32 m0, s63
	v_lshl_add_u64 v[8:9], s[20:21], 0, v[184:185]
	global_load_lds_dwordx4 v182, s[36:37]
	v_readlane_b32 s98, v255, 21
	s_cmp_eq_u32 s98, 0
	s_cbranch_scc1 .Lstat_done_2
	s_mov_b64 s[100:101], exec
	v_readlane_b32 s98, v254, 59
	v_readlane_b32 s99, v254, 60
	s_and_b64 s[98:99], s[100:101], s[98:99]
	s_mov_b64 exec, s[98:99]
	s_cbranch_execz .Lstat_skip_2
	v_lshl_add_u64 v[134:135], s[8:9], 0, v[198:199]
	global_load_dwordx4 v[100:103], v[134:135], off
	global_load_dwordx4 v[104:107], v[134:135], off offset:16
	global_load_dwordx4 v[108:111], v[134:135], off offset:32
	global_load_dwordx4 v[112:115], v[134:135], off offset:48
	global_load_dwordx4 v[116:119], v[134:135], off offset:64
	global_load_dwordx4 v[120:123], v[134:135], off offset:80
	global_load_dwordx4 v[124:127], v[134:135], off offset:96
	global_load_dwordx4 v[128:131], v[134:135], off offset:112
	s_mov_b32 s98, 0x3a800000
	s_waitcnt vmcnt(0) lgkmcnt(0)
	v_pk_add_f32 v[100:101], v[100:101], v[102:103]
	v_pk_add_f32 v[104:105], v[104:105], v[106:107]
	v_pk_add_f32 v[108:109], v[108:109], v[110:111]
	v_pk_add_f32 v[112:113], v[112:113], v[114:115]
	v_pk_add_f32 v[116:117], v[116:117], v[118:119]
	v_pk_add_f32 v[120:121], v[120:121], v[122:123]
	v_pk_add_f32 v[124:125], v[124:125], v[126:127]
	v_pk_add_f32 v[128:129], v[128:129], v[130:131]
	v_pk_add_f32 v[136:137], v[100:101], 0 op_sel_hi:[1,0]
	s_nop 0
	v_pk_add_f32 v[136:137], v[136:137], v[104:105]
	s_nop 0
	v_pk_add_f32 v[136:137], v[136:137], v[108:109]
	s_nop 0
	v_pk_add_f32 v[136:137], v[136:137], v[112:113]
	s_nop 0
	v_pk_add_f32 v[136:137], v[136:137], v[116:117]
	s_nop 0
	v_pk_add_f32 v[136:137], v[136:137], v[120:121]
	s_nop 0
	v_pk_add_f32 v[136:137], v[136:137], v[124:125]
	s_nop 0
	v_pk_add_f32 v[138:139], v[136:137], v[128:129]
	s_nop 0
	v_pk_mul_f32 v[138:139], v[138:139], s[98:99] op_sel_hi:[1,0]
	s_nop 0
	v_fma_f32 v132, -v138, v138, v139
	v_max_f32_e32 v132, 0, v132
	v_add_f32_e32 v132, 0x3727c5ac, v132
	v_cmp_gt_f32_e32 vcc, 0x800000, v132
	v_mul_f32_e32 v139, 0x4b800000, v132
	s_nop 0
	v_cndmask_b32_e32 v132, v132, v139, vcc
	v_rsq_f32_e32 v132, v132
	s_nop 0
	v_mul_f32_e32 v139, 0x45800000, v132
	v_cndmask_b32_e32 v139, v132, v139, vcc
	ds_write_b64 v217, v[138:139]

.Lstat_done_2:
	v_lshl_add_u64 v[6:7], s[20:21], 0, v[182:183]
	v_lshl_add_u64 v[4:5], s[48:49], 0, v[184:185]
	s_cmp_lg_u32 s4, 1
	v_lshl_add_u64 v[2:3], s[48:49], 0, v[182:183]
	s_cbranch_scc1 .LBB0_393
	s_barrier

.LBB0_974:
	s_ashr_i32 s6, s12, 3
	s_and_b32 s13, s12, 7
	s_ashr_i32 s7, s6, 31
	s_lshl_b64 s[8:9], s[6:7], 10
	s_lshl_b32 s7, s13, 7
	s_or_b32 s7, s8, s7
	s_add_u32 s8, s7, 0x1000000
	s_addc_u32 s9, s9, 0
	v_lshl_add_u64 v[28:29], s[8:9], 0, v[2:3]
	v_lshlrev_b64 v[28:29], 1, v[28:29]
	s_and_saveexec_b64 s[10:11], vcc
	s_cbranch_execz .Lhs_ld1
	v_readlane_b32 s14, v253, 49
	v_readlane_b32 s15, v253, 50
	global_load_dword v68, v[10:11], off
	v_lshl_add_u64 v[72:73], s[18:19], 0, v[28:29]
	global_load_ushort v69, v[72:73], off
	v_lshl_add_u64 v[74:75], s[70:71], 0, v[28:29]
	global_load_ushort v70, v[74:75], off
	v_lshl_add_u64 v[76:77], s[14:15], 0, v[28:29]
	global_load_ushort v71, v[76:77], off
.Lhs_ld1:
	s_or_b64 exec, exec, s[10:11]
	s_add_i32 s6, s6, s3
	s_ashr_i32 s7, s6, 31
	v_lshl_add_u64 v[90:91], s[8:9], 1, v[4:5]
	s_lshl_b64 s[6:7], s[6:7], 19
	s_lshl_b32 s8, s13, 16
	s_or_b32 s6, s6, s8
	v_lshl_add_u64 v[32:33], v[6:7], 0, s[6:7]
	v_lshl_add_u64 v[30:31], v[8:9], 0, s[6:7]
	global_load_dwordx2 v[90:91], v[90:91], off
	v_lshl_add_u64 v[42:43], v[32:33], 0, v[12:13]
	global_load_dwordx4 v[100:103], v[42:43], off
	v_lshl_add_u64 v[44:45], v[32:33], 0, v[14:15]
	global_load_dwordx4 v[104:107], v[44:45], off
	v_lshl_add_u64 v[46:47], v[32:33], 0, v[16:17]
	global_load_dwordx4 v[108:111], v[46:47], off
	v_lshl_add_u64 v[48:49], v[32:33], 0, v[18:19]
	global_load_dwordx4 v[112:115], v[48:49], off
	v_lshl_add_u64 v[50:51], v[32:33], 0, v[20:21]
	global_load_dwordx4 v[116:119], v[50:51], off
	v_lshl_add_u64 v[52:53], v[32:33], 0, v[22:23]
	global_load_dwordx4 v[120:123], v[52:53], off
	v_lshl_add_u64 v[54:55], v[32:33], 0, v[24:25]
	global_load_dwordx4 v[124:127], v[54:55], off
	v_lshl_add_u64 v[56:57], v[32:33], 0, v[26:27]
	global_load_dwordx4 v[128:131], v[56:57], off
	s_and_saveexec_b64 s[10:11], vcc
	s_cbranch_execz .Lhs_w1
	s_waitcnt vmcnt(9)
	v_lshlrev_b32_e32 v70, 16, v70
	v_lshlrev_b32_e32 v71, 16, v71
	ds_write2st64_b32 v1, v70, v71 offset1:2
.Lhs_w1:
	s_or_b64 exec, exec, s[10:11]
	s_waitcnt lgkmcnt(0)
	s_barrier
	ds_read_b32 v132, v34 offset:512
	ds_read_b32 v134, v34
	ds_read_b32 v136, v34 offset:576
	ds_read_b32 v138, v34 offset:64
	ds_read_b32 v140, v34 offset:640
	ds_read_b32 v142, v34 offset:128
	ds_read_b32 v144, v34 offset:704
	ds_read_b32 v146, v34 offset:192
	s_waitcnt lgkmcnt(7)
	ds_read_b32 v148, v34 offset:768
	ds_read_b32 v150, v34 offset:256
	ds_read_b32 v152, v34 offset:832
	ds_read_b32 v154, v34 offset:320
	ds_read_b32 v156, v34 offset:896
	ds_read_b32 v158, v34 offset:384
	ds_read_b32 v160, v34 offset:960
	ds_read_b32 v162, v34 offset:448
	s_waitcnt vmcnt(8)
	v_lshlrev_b32_e32 v37, 16, v90
	v_and_b32_e32 v39, 0xffff0000, v90
	v_lshlrev_b32_e32 v38, 16, v91
	v_and_b32_e32 v40, 0xffff0000, v91
	s_waitcnt lgkmcnt(0)
	s_waitcnt vmcnt(7)
	v_sub_f32_e32 v73, v39, v101
	v_sub_f32_e32 v72, v37, v100
	v_sub_f32_e32 v75, v40, v103
	v_sub_f32_e32 v74, v38, v102
	v_pk_fma_f32 v[102:103], v[74:75], v[132:133], v[102:103] op_sel_hi:[1,0,1]
	v_pk_fma_f32 v[100:101], v[72:73], v[132:133], v[100:101] op_sel_hi:[1,0,1]
	v_lshl_add_u64 v[42:43], v[30:31], 0, v[12:13]
	global_store_dwordx4 v[42:43], v[100:103], off
	v_pk_fma_f32 v[76:77], v[100:101], v[134:135], 0 op_sel_hi:[1,0,0]
	v_pk_fma_f32 v[78:79], v[102:103], v[134:135], 0 op_sel_hi:[1,0,0]
	s_waitcnt vmcnt(7)
	v_sub_f32_e32 v73, v39, v105
	v_sub_f32_e32 v72, v37, v104
	v_sub_f32_e32 v75, v40, v107
	v_sub_f32_e32 v74, v38, v106
	v_pk_fma_f32 v[106:107], v[74:75], v[136:137], v[106:107] op_sel_hi:[1,0,1]
	v_pk_fma_f32 v[104:105], v[72:73], v[136:137], v[104:105] op_sel_hi:[1,0,1]
	v_lshl_add_u64 v[44:45], v[30:31], 0, v[14:15]
	global_store_dwordx4 v[44:45], v[104:107], off
	v_pk_fma_f32 v[78:79], v[106:107], v[138:139], v[78:79] op_sel_hi:[1,0,1]
	v_pk_fma_f32 v[76:77], v[104:105], v[138:139], v[76:77] op_sel_hi:[1,0,1]
	s_waitcnt vmcnt(7)
	v_sub_f32_e32 v73, v39, v109
	v_sub_f32_e32 v72, v37, v108
	v_sub_f32_e32 v75, v40, v111
	v_sub_f32_e32 v74, v38, v110
	v_pk_fma_f32 v[110:111], v[74:75], v[140:141], v[110:111] op_sel_hi:[1,0,1]
	v_pk_fma_f32 v[108:109], v[72:73], v[140:141], v[108:109] op_sel_hi:[1,0,1]
	v_lshl_add_u64 v[46:47], v[30:31], 0, v[16:17]
	global_store_dwordx4 v[46:47], v[108:111], off
	v_pk_fma_f32 v[78:79], v[110:111], v[142:143], v[78:79] op_sel_hi:[1,0,1]
	v_pk_fma_f32 v[76:77], v[108:109], v[142:143], v[76:77] op_sel_hi:[1,0,1]
	s_waitcnt vmcnt(7)
	v_sub_f32_e32 v73, v39, v113
	v_sub_f32_e32 v72, v37, v112
	v_sub_f32_e32 v75, v40, v115
	v_sub_f32_e32 v74, v38, v114
	v_pk_fma_f32 v[114:115], v[74:75], v[144:145], v[114:115] op_sel_hi:[1,0,1]
	v_pk_fma_f32 v[112:113], v[72:73], v[144:145], v[112:113] op_sel_hi:[1,0,1]
	v_lshl_add_u64 v[48:49], v[30:31], 0, v[18:19]
	global_store_dwordx4 v[48:49], v[112:115], off
	v_pk_fma_f32 v[78:79], v[114:115], v[146:147], v[78:79] op_sel_hi:[1,0,1]
	v_pk_fma_f32 v[76:77], v[112:113], v[146:147], v[76:77] op_sel_hi:[1,0,1]
	s_waitcnt vmcnt(7)
	v_sub_f32_e32 v73, v39, v117
	v_sub_f32_e32 v72, v37, v116
	v_sub_f32_e32 v75, v40, v119
	v_sub_f32_e32 v74, v38, v118
	v_pk_fma_f32 v[118:119], v[74:75], v[148:149], v[118:119] op_sel_hi:[1,0,1]
	v_pk_fma_f32 v[116:117], v[72:73], v[148:149], v[116:117] op_sel_hi:[1,0,1]
	v_lshl_add_u64 v[50:51], v[30:31], 0, v[20:21]
	global_store_dwordx4 v[50:51], v[116:119], off
	v_pk_fma_f32 v[78:79], v[118:119], v[150:151], v[78:79] op_sel_hi:[1,0,1]
	v_pk_fma_f32 v[76:77], v[116:117], v[150:151], v[76:77] op_sel_hi:[1,0,1]
	s_waitcnt vmcnt(7)
	v_sub_f32_e32 v73, v39, v121
	v_sub_f32_e32 v72, v37, v120
	v_sub_f32_e32 v75, v40, v123
	v_sub_f32_e32 v74, v38, v122
	v_pk_fma_f32 v[122:123], v[74:75], v[152:153], v[122:123] op_sel_hi:[1,0,1]
	v_pk_fma_f32 v[120:121], v[72:73], v[152:153], v[120:121] op_sel_hi:[1,0,1]
	v_lshl_add_u64 v[52:53], v[30:31], 0, v[22:23]
	global_store_dwordx4 v[52:53], v[120:123], off
	v_pk_fma_f32 v[78:79], v[122:123], v[154:155], v[78:79] op_sel_hi:[1,0,1]
	v_pk_fma_f32 v[76:77], v[120:121], v[154:155], v[76:77] op_sel_hi:[1,0,1]
	s_waitcnt vmcnt(7)
	v_sub_f32_e32 v73, v39, v125
	v_sub_f32_e32 v72, v37, v124
	v_sub_f32_e32 v75, v40, v127
	v_sub_f32_e32 v74, v38, v126
	v_pk_fma_f32 v[126:127], v[74:75], v[156:157], v[126:127] op_sel_hi:[1,0,1]
	v_pk_fma_f32 v[124:125], v[72:73], v[156:157], v[124:125] op_sel_hi:[1,0,1]
	v_lshl_add_u64 v[54:55], v[30:31], 0, v[24:25]
	global_store_dwordx4 v[54:55], v[124:127], off
	v_pk_fma_f32 v[78:79], v[126:127], v[158:159], v[78:79] op_sel_hi:[1,0,1]
	v_pk_fma_f32 v[76:77], v[124:125], v[158:159], v[76:77] op_sel_hi:[1,0,1]
	s_waitcnt vmcnt(7)
	v_sub_f32_e32 v73, v39, v129
	v_sub_f32_e32 v72, v37, v128
	v_sub_f32_e32 v75, v40, v131
	v_sub_f32_e32 v74, v38, v130
	v_pk_fma_f32 v[130:131], v[74:75], v[160:161], v[130:131] op_sel_hi:[1,0,1]
	v_pk_fma_f32 v[128:129], v[72:73], v[160:161], v[128:129] op_sel_hi:[1,0,1]
	v_lshl_add_u64 v[56:57], v[30:31], 0, v[26:27]
	global_store_dwordx4 v[56:57], v[128:131], off
	v_pk_fma_f32 v[78:79], v[130:131], v[162:163], v[78:79] op_sel_hi:[1,0,1]
	v_pk_fma_f32 v[76:77], v[128:129], v[162:163], v[76:77] op_sel_hi:[1,0,1]
	ds_write_b128 v35, v[76:79] offset:1024
	v_mov_b32_e32 v30, 0
	s_waitcnt lgkmcnt(0)
	s_barrier
	s_and_saveexec_b64 s[8:9], vcc
	s_cbranch_execz .LBB0_980
	ds_read2st64_b32 v[30:31], v1 offset0:4 offset1:6
	v_xor_b32_e32 v33, 1, v216
	s_waitcnt lgkmcnt(0)
	v_add_f32_e32 v30, 0, v30
	v_add_f32_e32 v32, v30, v31
	ds_read2st64_b32 v[30:31], v1 offset0:8 offset1:10
	s_waitcnt lgkmcnt(0)
	v_add_f32_e32 v30, v32, v30
	v_add_f32_e32 v32, v30, v31
	ds_read2st64_b32 v[30:31], v1 offset0:12 offset1:14
	s_waitcnt lgkmcnt(0)
	v_add_f32_e32 v30, v32, v30
	v_add_f32_e32 v32, v30, v31
	ds_read2st64_b32 v[30:31], v1 offset0:16 offset1:18
	s_waitcnt lgkmcnt(0)
	v_add_f32_e32 v30, v32, v30
	v_add_f32_e32 v32, v30, v31
	ds_read2st64_b32 v[30:31], v1 offset0:20 offset1:22
	s_waitcnt lgkmcnt(0)
	v_add_f32_e32 v30, v32, v30
	v_add_f32_e32 v32, v30, v31
	ds_read2st64_b32 v[30:31], v1 offset0:24 offset1:26
	s_waitcnt lgkmcnt(0)
	v_add_f32_e32 v30, v32, v30
	v_add_f32_e32 v32, v30, v31
	ds_read2st64_b32 v[30:31], v1 offset0:28 offset1:30
	s_waitcnt lgkmcnt(0)
	v_add_f32_e32 v30, v32, v30
	v_add_f32_e32 v32, v30, v31
	ds_read2st64_b32 v[30:31], v1 offset0:32 offset1:34
	s_waitcnt lgkmcnt(0)
	v_add_f32_e32 v30, v32, v30
	v_and_b32_e32 v32, 64, v216
	v_add_u32_e32 v32, 64, v32
	v_cmp_lt_i32_e64 s[6:7], v33, v32
	v_add_f32_e32 v30, v30, v31
	v_mul_f32_e32 v31, v30, v30
	v_cndmask_b32_e64 v33, v216, v33, s[6:7]
	v_lshlrev_b32_e32 v33, 2, v33
	ds_bpermute_b32 v31, v33, v31
	v_xor_b32_e32 v33, 2, v216
	v_cmp_lt_i32_e64 s[6:7], v33, v32
	s_waitcnt lgkmcnt(0)
	v_fmac_f32_e32 v31, v30, v30
	v_cndmask_b32_e64 v33, v216, v33, s[6:7]
	v_lshlrev_b32_e32 v33, 2, v33
	ds_bpermute_b32 v33, v33, v31
	s_waitcnt lgkmcnt(0)
	v_add_f32_e32 v31, v31, v33
	v_xor_b32_e32 v33, 4, v216
	v_cmp_lt_i32_e64 s[6:7], v33, v32
	s_nop 1
	v_cndmask_b32_e64 v33, v216, v33, s[6:7]
	v_lshlrev_b32_e32 v33, 2, v33
	ds_bpermute_b32 v33, v33, v31
	s_waitcnt lgkmcnt(0)
	v_add_f32_e32 v31, v31, v33
	v_xor_b32_e32 v33, 8, v216
	v_cmp_lt_i32_e64 s[6:7], v33, v32
	s_nop 1
	v_cndmask_b32_e64 v33, v216, v33, s[6:7]
	v_lshlrev_b32_e32 v33, 2, v33
	ds_bpermute_b32 v33, v33, v31
	s_waitcnt lgkmcnt(0)
	v_add_f32_e32 v31, v31, v33
	v_xor_b32_e32 v33, 16, v216
	v_cmp_lt_i32_e64 s[6:7], v33, v32
	s_nop 1
	v_cndmask_b32_e64 v33, v216, v33, s[6:7]
	v_lshlrev_b32_e32 v33, 2, v33
	ds_bpermute_b32 v33, v33, v31
	s_waitcnt lgkmcnt(0)
	v_add_f32_e32 v31, v31, v33
	v_xor_b32_e32 v33, 32, v216
	v_cmp_lt_i32_e64 s[6:7], v33, v32
	s_nop 1
	v_cndmask_b32_e64 v32, v216, v33, s[6:7]
	v_lshlrev_b32_e32 v32, 2, v32
	ds_bpermute_b32 v32, v32, v31
	s_and_saveexec_b64 s[6:7], s[4:5]
	s_cbranch_execz .LBB0_979
	s_waitcnt lgkmcnt(0)
	v_add_f32_e32 v31, v31, v32
	ds_write_b32 v36, v31 offset:9216

.LBB0_980:
	s_or_b64 exec, exec, s[8:9]
	s_waitcnt lgkmcnt(0)
	s_barrier
	s_and_saveexec_b64 s[8:9], vcc
	s_cbranch_execz .LBB0_973
	ds_read_b64 v[32:33], v0 offset:9216
	s_waitcnt lgkmcnt(0)
	v_add_f32_e32 v31, v32, v33
	v_fmamk_f32 v31, v31, 0x3c000000, v220
	v_cmp_gt_f32_e64 s[6:7], s83, v31
	v_mul_f32_e32 v32, 0x4b800000, v31
	s_nop 0
	v_cndmask_b32_e64 v31, v31, v32, s[6:7]
	v_rsq_f32_e32 v31, v31
	s_nop 0
	v_mul_f32_e32 v32, 0x45800000, v31
	v_cndmask_b32_e64 v31, v31, v32, s[6:7]
	v_mul_f32_e32 v30, v30, v31
	v_mul_f32_e32 v32, v68, v30
	v_lshl_add_u64 v[28:29], s[16:17], 0, v[28:29]
	v_lshlrev_b32_e32 v30, 16, v69
	v_mul_f32_e32 v30, v32, v30
	v_bfe_u32 v31, v30, 16, 1
	v_add3_u32 v30, v30, v31, s34
	global_store_short_d16_hi v[28:29], v30, off
	s_branch .LBB0_973

.LBB0_1094:
	s_add_u32 s52, s28, 0x8288000
	s_addc_u32 s53, s29, 0
	s_add_u32 s3, s28, s18
	s_addc_u32 s5, s29, s19
	s_add_u32 s4, s3, 0x2000000
	s_addc_u32 s5, s5, 0
	s_add_u32 s3, s28, s20
	s_addc_u32 s27, s29, s21
	s_add_u32 s46, s3, 0x6218000
	s_addc_u32 s47, s27, 0
	s_add_u32 s48, s3, 0x622e000
	s_addc_u32 s49, s27, 0
	s_add_u32 s50, s28, 0x16a54000
	s_addc_u32 s51, s29, 0
	v_readlane_b32 s28, v254, 25
	v_mov_b32_e32 v18, v213
	v_readlane_b32 s29, v254, 26
	s_waitcnt lgkmcnt(0)
	s_barrier
	s_andn2_b64 vcc, exec, s[28:29]
	v_readfirstlane_b32 s38, v18
	s_cbranch_vccnz .LBB0_1104
	v_lshlrev_b32_e32 v1, 4, v18
	v_add_u32_e32 v2, 0x2000, v1
	v_ashrrev_i32_e32 v3, 31, v2
	v_lshrrev_b32_e32 v3, 22, v3
	v_add_u32_e32 v3, v2, v3
	v_ashrrev_i32_e32 v10, 10, v3
	v_mul_i32_i24_e32 v3, 0x400, v10
	v_sub_u32_e32 v2, v2, v3
	v_lshrrev_b32_e32 v3, 4, v2
	v_bitop3_b32 v2, v3, v2, 32 bitop3:0x6c
	v_ashrrev_i32_e32 v3, 31, v2
	v_lshrrev_b32_e32 v3, 26, v3
	v_add_u32_e32 v3, v2, v3
	v_ashrrev_i32_e32 v11, 6, v3
	v_and_b32_e32 v3, 0xc0, v3
	v_sub_u32_e32 v2, v2, v3
	v_ashrrev_i16_sdwa v2, v219, sext(v2) dst_sel:DWORD dst_unused:UNUSED_PAD src0_sel:DWORD src1_sel:BYTE_0
	v_bfe_i32 v13, v2, 0, 16
	v_bfe_i32 v2, v18, 27, 1
	v_lshrrev_b32_e32 v2, 22, v2
	v_add_u32_e32 v2, v1, v2
	v_and_b32_e32 v2, 0xfffffc00, v2
	v_sub_u32_e32 v1, v1, v2
	v_lshrrev_b32_e32 v2, 4, v1
	v_bitop3_b32 v1, v2, v1, 32 bitop3:0x6c
	v_ashrrev_i32_e32 v3, 31, v18
	v_lshlrev_b32_e32 v4, 3, v10
	v_ashrrev_i32_e32 v2, 31, v1
	v_lshrrev_b32_e32 v3, 26, v3
	v_and_b32_e32 v4, 0x1ffff0, v4
	v_lshlrev_b32_e32 v5, 5, v10
	v_lshrrev_b32_e32 v2, 26, v2
	v_add_u32_e32 v3, v18, v3
	v_add_u32_e32 v4, v11, v4
	v_and_b32_e32 v12, 32, v5
	v_add_u32_e32 v2, v1, v2
	v_ashrrev_i32_e32 v15, 6, v3
	s_ashr_i32 s3, s38, 6
	v_lshl_or_b32 v4, v4, 10, v12
	v_ashrrev_i32_e32 v14, 6, v2
	v_lshlrev_b32_e32 v3, 3, v15
	v_and_b32_e32 v2, 0xc0, v2
	s_ashr_i32 s27, s38, 8
	s_lshl_b32 s68, s3, 10
	v_add_lshl_u32 v162, v4, v13, 1
	v_and_b32_e32 v3, 0x1ffff0, v3
	v_lshlrev_b32_e32 v4, 5, v15
	v_sub_u32_e32 v1, v1, v2
	v_readlane_b32 s28, v252, 53
	v_add_u32_e32 v3, v14, v3
	v_and_b32_e32 v16, 32, v4
	v_ashrrev_i16_sdwa v1, v219, sext(v1) dst_sel:DWORD dst_unused:UNUSED_PAD src0_sel:DWORD src1_sel:BYTE_0
	v_readlane_b32 s29, v252, 54
	s_add_u32 s54, s4, s28
	v_lshl_or_b32 v3, v3, 10, v16
	v_bfe_i32 v17, v1, 0, 16
	s_addc_u32 s55, s5, s29
	s_add_i32 s69, s68, 0
	v_add_lshl_u32 v164, v3, v17, 1
	s_add_i32 m0, s69, 0x10000
	v_readlane_b32 s28, v252, 50
	global_load_lds_dwordx4 v164, s[54:55]
	s_add_i32 m0, s69, 0x12000
	s_add_u32 s56, s52, s28
	global_load_lds_dwordx4 v162, s[54:55]
	s_addc_u32 s57, s53, 0
	s_mov_b32 m0, s69
	s_add_i32 s70, s69, 0x2000
	global_load_lds_dwordx4 v164, s[56:57]
	s_mov_b32 m0, s70
	s_add_u32 s28, s54, 0x40000
	global_load_lds_dwordx4 v162, s[56:57]
	s_addc_u32 s29, s55, 0
	s_add_i32 m0, s69, 0x14000
	v_mov_b32_e32 v165, v0
	global_load_lds_dwordx4 v164, s[28:29]
	s_add_i32 m0, s69, 0x16000
	v_mov_b32_e32 v163, v0
	global_load_lds_dwordx4 v162, s[28:29]
	s_add_u32 s28, s56, 0x40000
	s_addc_u32 s29, s57, 0
	s_add_i32 s71, s69, 0x4000
	s_mov_b32 m0, s71
	s_add_i32 s72, s69, 0x6000
	global_load_lds_dwordx4 v164, s[28:29]
	s_mov_b32 m0, s72
	v_lshl_add_u64 v[8:9], s[54:55], 0, v[164:165]
	global_load_lds_dwordx4 v162, s[28:29]
	s_mov_b64 s[100:101], exec
	v_readlane_b32 s98, v254, 59
	v_readlane_b32 s99, v254, 60
	s_and_b64 s[98:99], s[100:101], s[98:99]
	s_mov_b64 exec, s[98:99]
	s_cbranch_execz .Lstat_skip_3
	v_lshl_add_u64 v[134:135], s[42:43], 0, v[198:199]
	global_load_dwordx4 v[100:103], v[134:135], off
	global_load_dwordx4 v[104:107], v[134:135], off offset:16
	global_load_dwordx4 v[108:111], v[134:135], off offset:32
	global_load_dwordx4 v[112:115], v[134:135], off offset:48
	global_load_dwordx4 v[116:119], v[134:135], off offset:64
	global_load_dwordx4 v[120:123], v[134:135], off offset:80
	global_load_dwordx4 v[124:127], v[134:135], off offset:96
	global_load_dwordx4 v[128:131], v[134:135], off offset:112
	s_mov_b32 s98, 0x3a800000
	s_waitcnt vmcnt(0) lgkmcnt(0)
	v_pk_add_f32 v[100:101], v[100:101], v[102:103]
	v_pk_add_f32 v[104:105], v[104:105], v[106:107]
	v_pk_add_f32 v[108:109], v[108:109], v[110:111]
	v_pk_add_f32 v[112:113], v[112:113], v[114:115]
	v_pk_add_f32 v[116:117], v[116:117], v[118:119]
	v_pk_add_f32 v[120:121], v[120:121], v[122:123]
	v_pk_add_f32 v[124:125], v[124:125], v[126:127]
	v_pk_add_f32 v[128:129], v[128:129], v[130:131]
	v_pk_add_f32 v[136:137], v[100:101], 0 op_sel_hi:[1,0]
	s_nop 0
	v_pk_add_f32 v[136:137], v[136:137], v[104:105]
	s_nop 0
	v_pk_add_f32 v[136:137], v[136:137], v[108:109]
	s_nop 0
	v_pk_add_f32 v[136:137], v[136:137], v[112:113]
	s_nop 0
	v_pk_add_f32 v[136:137], v[136:137], v[116:117]
	s_nop 0
	v_pk_add_f32 v[136:137], v[136:137], v[120:121]
	s_nop 0
	v_pk_add_f32 v[136:137], v[136:137], v[124:125]
	s_nop 0
	v_pk_add_f32 v[138:139], v[136:137], v[128:129]
	s_nop 0
	v_pk_mul_f32 v[138:139], v[138:139], s[98:99] op_sel_hi:[1,0]
	s_nop 0
	v_fma_f32 v132, -v138, v138, v139
	v_max_f32_e32 v132, 0, v132
	v_add_f32_e32 v132, 0x3727c5ac, v132
	v_cmp_gt_f32_e32 vcc, 0x800000, v132
	v_mul_f32_e32 v139, 0x4b800000, v132
	s_nop 0
	v_cndmask_b32_e32 v132, v132, v139, vcc
	v_rsq_f32_e32 v132, v132
	s_nop 0
	v_mul_f32_e32 v139, 0x45800000, v132
	v_cndmask_b32_e32 v139, v132, v139, vcc
	ds_write_b64 v217, v[138:139]

.Lstat_done_3:
	v_lshl_add_u64 v[6:7], s[54:55], 0, v[162:163]
	v_lshl_add_u64 v[4:5], s[56:57], 0, v[164:165]
	s_cmp_lg_u32 s27, 1
	v_lshl_add_u64 v[2:3], s[56:57], 0, v[162:163]
	s_cbranch_scc1 .LBB0_1097
	s_barrier

.LBB0_1166:
.LBB0_1168:
	s_waitcnt lgkmcnt(0)
	s_barrier
.LBB0_1169:
	s_add_u32 s58, s4, s36
	s_addc_u32 s59, s5, s37
	s_add_u32 s60, s4, s28
	s_addc_u32 s61, s5, s29
	v_readlane_b32 s4, v253, 39
	s_waitcnt vmcnt(0)
	v_mov_b32_e32 v19, v213
	v_readlane_b32 s5, v253, 40
	s_andn2_b64 vcc, exec, s[4:5]
	v_readfirstlane_b32 s76, v19
	s_cbranch_vccnz .LBB0_1223
	v_lshlrev_b32_e32 v2, 4, v19
	v_add_u32_e32 v1, 0x2000, v2
	v_ashrrev_i32_e32 v3, 31, v1
	v_lshrrev_b32_e32 v3, 22, v3
	v_add_u32_e32 v3, v1, v3
	v_ashrrev_i32_e32 v3, 10, v3
	v_mul_i32_i24_e32 v4, 0x400, v3
	v_sub_u32_e32 v1, v1, v4
	v_lshrrev_b32_e32 v4, 4, v1
	v_bitop3_b32 v4, v4, v1, 32 bitop3:0x6c
	v_ashrrev_i32_e32 v1, 31, v4
	v_lshrrev_b32_e32 v1, 26, v1
	v_add_u32_e32 v5, v4, v1
	v_lshlrev_b32_e32 v6, 3, v3
	v_ashrrev_i32_e32 v1, 6, v5
	v_and_b32_e32 v6, 0x7ffffff0, v6
	v_and_b32_e32 v5, 0xc0, v5
	v_add_u32_e32 v1, v1, v6
	v_lshlrev_b32_e32 v3, 5, v3
	v_sub_u32_e32 v4, v4, v5
	v_mul_lo_u32 v1, v1, s75
	v_and_b32_e32 v14, 32, v3
	v_ashrrev_i16_sdwa v4, v219, sext(v4) dst_sel:DWORD dst_unused:UNUSED_PAD src0_sel:DWORD src1_sel:BYTE_0
	v_or_b32_e32 v3, v1, v14
	v_bfe_i32 v15, v4, 0, 16
	v_add_lshl_u32 v200, v3, v15, 1
	v_bfe_i32 v3, v19, 27, 1
	v_lshrrev_b32_e32 v3, 22, v3
	v_add_u32_e32 v3, v2, v3
	v_and_b32_e32 v3, 0xfffffc00, v3
	v_sub_u32_e32 v2, v2, v3
	v_lshrrev_b32_e32 v3, 4, v2
	v_ashrrev_i32_e32 v5, 31, v19
	v_bitop3_b32 v2, v3, v2, 32 bitop3:0x6c
	v_lshrrev_b32_e32 v5, 26, v5
	v_ashrrev_i32_e32 v3, 31, v2
	v_add_u32_e32 v5, v19, v5
	v_lshrrev_b32_e32 v3, 26, v3
	v_ashrrev_i32_e32 v5, 6, v5
	v_add_u32_e32 v3, v2, v3
	v_lshlrev_b32_e32 v6, 3, v5
	v_ashrrev_i32_e32 v4, 6, v3
	v_and_b32_e32 v6, 0x7ffffff0, v6
	s_ashr_i32 s27, s76, 6
	s_lshl_b32 s77, s75, 9
	v_add_u32_e32 v4, v4, v6
	v_and_b32_e32 v3, 0xc0, v3
	v_readlane_b32 s36, v252, 51
	s_ashr_i32 s3, s76, 8
	s_lshl_b32 s4, s75, 8
	s_lshl_b32 s78, s27, 10
	v_mul_lo_u32 v16, v4, s75
	v_lshlrev_b32_e32 v4, 5, v5
	v_sub_u32_e32 v2, v2, v3
	s_mul_hi_i32 s29, s77, s36
	s_mul_i32 s36, s77, s36
	v_and_b32_e32 v17, 32, v4
	v_ashrrev_i16_sdwa v2, v219, sext(v2) dst_sel:DWORD dst_unused:UNUSED_PAD src0_sel:DWORD src1_sel:BYTE_0
	v_readlane_b32 s37, v252, 52
	s_add_u32 s36, s64, s36
	v_or_b32_e32 v4, v16, v17
	v_bfe_i32 v18, v2, 0, 16
	s_addc_u32 s37, s65, s29
	s_add_i32 s79, s78, 0
	v_add_lshl_u32 v202, v4, v18, 1
	v_readlane_b32 s28, v254, 29
	s_add_i32 m0, s79, 0x10000
	s_mul_i32 s28, s77, s28
	global_load_lds_dwordx4 v202, s[36:37]
	s_add_i32 m0, s79, 0x12000
	s_add_u32 s42, s62, s28
	global_load_lds_dwordx4 v200, s[36:37]
	s_addc_u32 s43, s63, 0
	s_mov_b32 m0, s79
	s_add_i32 s80, s79, 0x2000
	global_load_lds_dwordx4 v202, s[42:43]
	s_mov_b32 m0, s80
	s_add_u32 s28, s36, s4
	global_load_lds_dwordx4 v200, s[42:43]
	s_addc_u32 s29, s37, 0
	s_add_i32 m0, s79, 0x14000
	v_mov_b32_e32 v203, v0
	v_mov_b32_e32 v201, v0
	global_load_lds_dwordx4 v202, s[28:29]
	s_add_i32 m0, s79, 0x16000
	v_lshl_add_u64 v[10:11], s[28:29], 0, v[202:203]
	v_lshl_add_u64 v[12:13], s[28:29], 0, v[200:201]
	global_load_lds_dwordx4 v200, s[28:29]
	s_add_u32 s28, s42, s4
	s_addc_u32 s29, s43, 0
	s_add_i32 s81, s79, 0x4000
	s_mov_b32 m0, s81
	s_add_i32 s82, s79, 0x6000
	global_load_lds_dwordx4 v202, s[28:29]
	s_mov_b32 m0, s82
	s_mov_b32 s5, s39
	global_load_lds_dwordx4 v200, s[28:29]
	s_cmp_eq_u64 s[50:51], 0
	s_cbranch_scc1 .Lstat_done_4
	s_mov_b64 s[100:101], exec
	v_readlane_b32 s98, v254, 59
	v_readlane_b32 s99, v254, 60
	s_and_b64 s[98:99], s[100:101], s[98:99]
	s_mov_b64 exec, s[98:99]
	s_cbranch_execz .Lstat_skip_4
	v_lshl_add_u64 v[134:135], s[50:51], 0, v[198:199]
	global_load_dwordx4 v[100:103], v[134:135], off
	global_load_dwordx4 v[104:107], v[134:135], off offset:16
	global_load_dwordx4 v[108:111], v[134:135], off offset:32
	global_load_dwordx4 v[112:115], v[134:135], off offset:48
	global_load_dwordx4 v[116:119], v[134:135], off offset:64
	global_load_dwordx4 v[120:123], v[134:135], off offset:80
	global_load_dwordx4 v[124:127], v[134:135], off offset:96
	global_load_dwordx4 v[128:131], v[134:135], off offset:112
	s_mov_b32 s98, 0x3a800000
	s_waitcnt vmcnt(0) lgkmcnt(0)
	v_pk_add_f32 v[100:101], v[100:101], v[102:103]
	v_pk_add_f32 v[104:105], v[104:105], v[106:107]
	v_pk_add_f32 v[108:109], v[108:109], v[110:111]
	v_pk_add_f32 v[112:113], v[112:113], v[114:115]
	v_pk_add_f32 v[116:117], v[116:117], v[118:119]
	v_pk_add_f32 v[120:121], v[120:121], v[122:123]
	v_pk_add_f32 v[124:125], v[124:125], v[126:127]
	v_pk_add_f32 v[128:129], v[128:129], v[130:131]
	v_pk_add_f32 v[136:137], v[100:101], 0 op_sel_hi:[1,0]
	s_nop 0
	v_pk_add_f32 v[136:137], v[136:137], v[104:105]
	s_nop 0
	v_pk_add_f32 v[136:137], v[136:137], v[108:109]
	s_nop 0
	v_pk_add_f32 v[136:137], v[136:137], v[112:113]
	s_nop 0
	v_pk_add_f32 v[136:137], v[136:137], v[116:117]
	s_nop 0
	v_pk_add_f32 v[136:137], v[136:137], v[120:121]
	s_nop 0
	v_pk_add_f32 v[136:137], v[136:137], v[124:125]
	s_nop 0
	v_pk_add_f32 v[138:139], v[136:137], v[128:129]
	s_nop 0
	v_pk_mul_f32 v[138:139], v[138:139], s[98:99] op_sel_hi:[1,0]
	s_nop 0
	v_fma_f32 v132, -v138, v138, v139
	v_max_f32_e32 v132, 0, v132
	v_add_f32_e32 v132, 0x3727c5ac, v132
	v_cmp_gt_f32_e32 vcc, 0x800000, v132
	v_mul_f32_e32 v139, 0x4b800000, v132
	s_nop 0
	v_cndmask_b32_e32 v132, v132, v139, vcc
	v_rsq_f32_e32 v132, v132
	s_nop 0
	v_mul_f32_e32 v139, 0x45800000, v132
	v_cndmask_b32_e32 v139, v132, v139, vcc
	ds_write_b64 v217, v[138:139]

.Lstat_done_4:
	v_lshl_add_u64 v[2:3], s[36:37], 0, v[202:203]
	v_lshl_add_u64 v[4:5], s[36:37], 0, v[200:201]
	v_lshl_add_u64 v[6:7], s[42:43], 0, v[202:203]
	v_lshl_add_u64 v[8:9], s[42:43], 0, v[200:201]
	s_cmp_lg_u32 s3, 1
	s_cbranch_scc1 .LBB0_1172
	s_barrier
